# fused-RMSNorm GEMM epilogues: the leading half computes its per-row sums of squares before the alignment barrier (under the trailing half's last MFMA segment)
# baseline (speedup 1.0000x reference)
.LBB0_741:
	s_add_u32 s12, s36, 0xfff80080
	s_addc_u32 s13, s37, -1
	s_add_i32 s14, 0, 0x10000
	s_cmp_eq_u32 s11, 28
	s_cselect_b32 s63, s5, s13
	s_cselect_b32 s62, s6, s12
	s_cselect_b32 s39, s7, s10
	s_cselect_b32 s38, s8, s9
	s_add_i32 s15, 0, 0x14000
	v_add_u32_e32 v144, s14, v230
	v_add_u32_e32 v160, s15, v230
	ds_read_b128 v[124:127], v144
	ds_read_b128 v[128:131], v144 offset:1024
	ds_read_b128 v[136:139], v144 offset:2048
	ds_read_b128 v[144:147], v144 offset:3072
	ds_read_b128 v[148:151], v160
	ds_read_b128 v[152:155], v160 offset:1024
	ds_read_b128 v[156:159], v160 offset:2048
	ds_read_b128 v[160:163], v160 offset:3072
	v_lshl_add_u64 v[196:197], s[36:37], 0, v[222:223]
	s_add_i32 m0, s21, 0xc000
	ds_read_b128 v[164:167], v243
	ds_read_b128 v[168:171], v243 offset:1024
	ds_read_b128 v[172:175], v243 offset:2048
	ds_read_b128 v[176:179], v243 offset:3072
	ds_read_b128 v[180:183], v243 offset:4096
	ds_read_b128 v[184:187], v243 offset:5120
	ds_read_b128 v[188:191], v243 offset:6144
	ds_read_b128 v[192:195], v243 offset:7168
	global_load_lds_dwordx4 v[196:197], off
	v_lshl_add_u64 v[196:197], s[36:37], 0, v[220:221]
	s_add_i32 m0, s21, 0xe000
	s_nop 0
	global_load_lds_dwordx4 v[196:197], off
	s_waitcnt vmcnt(8)
	s_waitcnt lgkmcnt(0)
	s_barrier
	s_setprio 1
	s_waitcnt lgkmcnt(0)
	v_mfma_f32_16x16x32_bf16 v[140:143], v[124:127], v[164:167], v[140:143]
	v_mfma_f32_16x16x32_bf16 v[132:135], v[136:139], v[164:167], v[132:135]
	v_mfma_f32_16x16x32_bf16 v[112:115], v[124:127], v[172:175], v[112:115]
	v_mfma_f32_16x16x32_bf16 v[108:111], v[136:139], v[172:175], v[108:111]
	v_mfma_f32_16x16x32_bf16 v[96:99], v[124:127], v[180:183], v[96:99]
	v_mfma_f32_16x16x32_bf16 v[92:95], v[136:139], v[180:183], v[92:95]
	v_mfma_f32_16x16x32_bf16 v[80:83], v[124:127], v[188:191], v[80:83]
	v_mfma_f32_16x16x32_bf16 v[76:79], v[136:139], v[188:191], v[76:79]
	v_mfma_f32_16x16x32_bf16 v[140:143], v[128:131], v[168:171], v[140:143]
	v_mfma_f32_16x16x32_bf16 v[132:135], v[144:147], v[168:171], v[132:135]
	v_mfma_f32_16x16x32_bf16 v[112:115], v[128:131], v[176:179], v[112:115]
	v_mfma_f32_16x16x32_bf16 v[108:111], v[144:147], v[176:179], v[108:111]
	v_mfma_f32_16x16x32_bf16 v[96:99], v[128:131], v[184:187], v[96:99]
	v_mfma_f32_16x16x32_bf16 v[92:95], v[144:147], v[184:187], v[92:95]
	v_mfma_f32_16x16x32_bf16 v[80:83], v[128:131], v[192:195], v[80:83]
	v_mfma_f32_16x16x32_bf16 v[76:79], v[144:147], v[192:195], v[76:79]
	s_setprio 0
	s_setprio 1
	v_mfma_f32_16x16x32_bf16 v[120:123], v[148:151], v[164:167], v[120:123]
	v_mfma_f32_16x16x32_bf16 v[116:119], v[156:159], v[164:167], v[116:119]
	v_mfma_f32_16x16x32_bf16 v[104:107], v[148:151], v[172:175], v[104:107]
	v_mfma_f32_16x16x32_bf16 v[100:103], v[156:159], v[172:175], v[100:103]
	v_mfma_f32_16x16x32_bf16 v[88:91], v[148:151], v[180:183], v[88:91]
	v_mfma_f32_16x16x32_bf16 v[84:87], v[156:159], v[180:183], v[84:87]
	v_mfma_f32_16x16x32_bf16 v[72:75], v[148:151], v[188:191], v[72:75]
	v_mfma_f32_16x16x32_bf16 v[68:71], v[156:159], v[188:191], v[68:71]
	v_mfma_f32_16x16x32_bf16 v[120:123], v[152:155], v[168:171], v[120:123]
	v_mfma_f32_16x16x32_bf16 v[116:119], v[160:163], v[168:171], v[116:119]
	v_mfma_f32_16x16x32_bf16 v[104:107], v[152:155], v[176:179], v[104:107]
	v_mfma_f32_16x16x32_bf16 v[100:103], v[160:163], v[176:179], v[100:103]
	v_mfma_f32_16x16x32_bf16 v[88:91], v[152:155], v[184:187], v[88:91]
	v_mfma_f32_16x16x32_bf16 v[84:87], v[160:163], v[184:187], v[84:87]
	v_mfma_f32_16x16x32_bf16 v[72:75], v[152:155], v[192:195], v[72:75]
	v_mfma_f32_16x16x32_bf16 v[68:71], v[160:163], v[192:195], v[68:71]
	s_setprio 0
	s_barrier
	s_add_i32 s12, s14, s82
	v_lshl_add_u64 v[196:197], s[38:39], 0, v[2:3]
	s_mov_b32 m0, s12
	ds_read_b128 v[164:167], v243 offset:16384
	ds_read_b128 v[168:171], v243 offset:17408
	ds_read_b128 v[172:175], v243 offset:18432
	ds_read_b128 v[176:179], v243 offset:19456
	ds_read_b128 v[180:183], v243 offset:20480
	ds_read_b128 v[184:187], v243 offset:21504
	ds_read_b128 v[188:191], v243 offset:22528
	ds_read_b128 v[192:195], v243 offset:23552
	global_load_lds_dwordx4 v[196:197], off
	s_add_i32 m0, s12, 0x2000
	s_add_u32 s12, s38, 0x80000
	v_lshl_add_u64 v[198:199], s[38:39], 0, v[218:219]
	s_addc_u32 s13, s39, 0
	s_add_i32 s14, s15, s82
	global_load_lds_dwordx4 v[198:199], off
	v_lshl_add_u64 v[200:201], s[12:13], 0, v[2:3]
	s_mov_b32 m0, s14
	v_lshl_add_u64 v[202:203], s[62:63], 0, v[216:217]
	global_load_lds_dwordx4 v[200:201], off
	v_lshl_add_u64 v[200:201], s[12:13], 0, v[218:219]
	s_add_i32 m0, s14, 0x2000
	s_nop 0
	global_load_lds_dwordx4 v[200:201], off
	v_lshl_add_u64 v[200:201], s[62:63], 0, v[0:1]
	s_mov_b32 m0, s21
	s_nop 0
	global_load_lds_dwordx4 v[200:201], off
	s_mov_b32 m0, s83
	s_nop 0
	global_load_lds_dwordx4 v[202:203], off
	s_waitcnt vmcnt(8)
	s_waitcnt lgkmcnt(0)
	s_barrier
	s_setprio 1
	s_waitcnt lgkmcnt(0)
	v_mfma_f32_16x16x32_bf16 v[64:67], v[124:127], v[164:167], v[64:67]
	v_mfma_f32_16x16x32_bf16 v[60:63], v[136:139], v[164:167], v[60:63]
	v_mfma_f32_16x16x32_bf16 v[48:51], v[124:127], v[172:175], v[48:51]
	v_mfma_f32_16x16x32_bf16 v[44:47], v[136:139], v[172:175], v[44:47]
	v_mfma_f32_16x16x32_bf16 v[32:35], v[124:127], v[180:183], v[32:35]
	v_mfma_f32_16x16x32_bf16 v[28:31], v[136:139], v[180:183], v[28:31]
	v_mfma_f32_16x16x32_bf16 v[16:19], v[124:127], v[188:191], v[16:19]
	v_mfma_f32_16x16x32_bf16 v[12:15], v[136:139], v[188:191], v[12:15]
	v_mfma_f32_16x16x32_bf16 v[64:67], v[128:131], v[168:171], v[64:67]
	v_mfma_f32_16x16x32_bf16 v[60:63], v[144:147], v[168:171], v[60:63]
	v_mfma_f32_16x16x32_bf16 v[48:51], v[128:131], v[176:179], v[48:51]
	v_mfma_f32_16x16x32_bf16 v[44:47], v[144:147], v[176:179], v[44:47]
	v_mfma_f32_16x16x32_bf16 v[32:35], v[128:131], v[184:187], v[32:35]
	v_mfma_f32_16x16x32_bf16 v[28:31], v[144:147], v[184:187], v[28:31]
	v_mfma_f32_16x16x32_bf16 v[16:19], v[128:131], v[192:195], v[16:19]
	v_mfma_f32_16x16x32_bf16 v[12:15], v[144:147], v[192:195], v[12:15]
	s_setprio 0
	s_setprio 1
	v_mfma_f32_16x16x32_bf16 v[56:59], v[148:151], v[164:167], v[56:59]
	v_mfma_f32_16x16x32_bf16 v[52:55], v[156:159], v[164:167], v[52:55]
	v_mfma_f32_16x16x32_bf16 v[40:43], v[148:151], v[172:175], v[40:43]
	v_mfma_f32_16x16x32_bf16 v[36:39], v[156:159], v[172:175], v[36:39]
	v_mfma_f32_16x16x32_bf16 v[24:27], v[148:151], v[180:183], v[24:27]
	v_mfma_f32_16x16x32_bf16 v[20:23], v[156:159], v[180:183], v[20:23]
	v_mfma_f32_16x16x32_bf16 v[8:11], v[148:151], v[188:191], v[8:11]
	v_mfma_f32_16x16x32_bf16 v[4:7], v[156:159], v[188:191], v[4:7]
	v_mfma_f32_16x16x32_bf16 v[56:59], v[152:155], v[168:171], v[56:59]
	v_mfma_f32_16x16x32_bf16 v[52:55], v[160:163], v[168:171], v[52:55]
	v_mfma_f32_16x16x32_bf16 v[40:43], v[152:155], v[176:179], v[40:43]
	v_mfma_f32_16x16x32_bf16 v[36:39], v[160:163], v[176:179], v[36:39]
	v_mfma_f32_16x16x32_bf16 v[24:27], v[152:155], v[184:187], v[24:27]
	v_mfma_f32_16x16x32_bf16 v[20:23], v[160:163], v[184:187], v[20:23]
	v_mfma_f32_16x16x32_bf16 v[8:11], v[152:155], v[192:195], v[8:11]
	v_mfma_f32_16x16x32_bf16 v[4:7], v[160:163], v[192:195], v[4:7]
	s_setprio 0
	s_barrier
	s_add_i32 s14, 0, 0x18000
	s_add_i32 s15, 0, 0x1c000
	v_add_u32_e32 v144, s14, v230
	v_add_u32_e32 v160, s15, v230
	ds_read_b128 v[124:127], v144
	ds_read_b128 v[128:131], v144 offset:1024
	ds_read_b128 v[136:139], v144 offset:2048
	ds_read_b128 v[144:147], v144 offset:3072
	ds_read_b128 v[148:151], v160
	ds_read_b128 v[152:155], v160 offset:1024
	ds_read_b128 v[156:159], v160 offset:2048
	ds_read_b128 v[160:163], v160 offset:3072
	s_add_u32 s12, s62, 0x80000
	s_addc_u32 s13, s63, 0
	s_mov_b32 m0, s84
	v_lshl_add_u64 v[204:205], s[12:13], 0, v[0:1]
	ds_read_b128 v[164:167], v243 offset:32768
	ds_read_b128 v[168:171], v243 offset:33792
	ds_read_b128 v[172:175], v243 offset:34816
	ds_read_b128 v[176:179], v243 offset:35840
	ds_read_b128 v[180:183], v243 offset:36864
	ds_read_b128 v[184:187], v243 offset:37888
	ds_read_b128 v[188:191], v243 offset:38912
	ds_read_b128 v[192:195], v243 offset:39936
	global_load_lds_dwordx4 v[204:205], off
	v_lshl_add_u64 v[204:205], s[12:13], 0, v[216:217]
	s_mov_b32 m0, s85
	s_nop 0
	global_load_lds_dwordx4 v[204:205], off
	s_waitcnt vmcnt(8)
	s_waitcnt lgkmcnt(0)
	s_barrier
	s_setprio 1
	s_waitcnt lgkmcnt(0)
	v_mfma_f32_16x16x32_bf16 v[140:143], v[124:127], v[164:167], v[140:143]
	v_mfma_f32_16x16x32_bf16 v[132:135], v[136:139], v[164:167], v[132:135]
	v_mfma_f32_16x16x32_bf16 v[112:115], v[124:127], v[172:175], v[112:115]
	v_mfma_f32_16x16x32_bf16 v[108:111], v[136:139], v[172:175], v[108:111]
	v_mfma_f32_16x16x32_bf16 v[96:99], v[124:127], v[180:183], v[96:99]
	v_mfma_f32_16x16x32_bf16 v[92:95], v[136:139], v[180:183], v[92:95]
	v_mfma_f32_16x16x32_bf16 v[80:83], v[124:127], v[188:191], v[80:83]
	v_mfma_f32_16x16x32_bf16 v[76:79], v[136:139], v[188:191], v[76:79]
	v_mfma_f32_16x16x32_bf16 v[140:143], v[128:131], v[168:171], v[140:143]
	v_mfma_f32_16x16x32_bf16 v[132:135], v[144:147], v[168:171], v[132:135]
	v_mfma_f32_16x16x32_bf16 v[112:115], v[128:131], v[176:179], v[112:115]
	v_mfma_f32_16x16x32_bf16 v[108:111], v[144:147], v[176:179], v[108:111]
	v_mfma_f32_16x16x32_bf16 v[96:99], v[128:131], v[184:187], v[96:99]
	v_mfma_f32_16x16x32_bf16 v[92:95], v[144:147], v[184:187], v[92:95]
	v_mfma_f32_16x16x32_bf16 v[80:83], v[128:131], v[192:195], v[80:83]
	v_mfma_f32_16x16x32_bf16 v[76:79], v[144:147], v[192:195], v[76:79]
	s_setprio 0
	s_setprio 1
	v_mfma_f32_16x16x32_bf16 v[120:123], v[148:151], v[164:167], v[120:123]
	v_mfma_f32_16x16x32_bf16 v[116:119], v[156:159], v[164:167], v[116:119]
	v_mfma_f32_16x16x32_bf16 v[104:107], v[148:151], v[172:175], v[104:107]
	v_mfma_f32_16x16x32_bf16 v[100:103], v[156:159], v[172:175], v[100:103]
	v_mfma_f32_16x16x32_bf16 v[88:91], v[148:151], v[180:183], v[88:91]
	v_mfma_f32_16x16x32_bf16 v[84:87], v[156:159], v[180:183], v[84:87]
	v_mfma_f32_16x16x32_bf16 v[72:75], v[148:151], v[188:191], v[72:75]
	v_mfma_f32_16x16x32_bf16 v[68:71], v[156:159], v[188:191], v[68:71]
	v_mfma_f32_16x16x32_bf16 v[120:123], v[152:155], v[168:171], v[120:123]
	v_mfma_f32_16x16x32_bf16 v[116:119], v[160:163], v[168:171], v[116:119]
	v_mfma_f32_16x16x32_bf16 v[104:107], v[152:155], v[176:179], v[104:107]
	v_mfma_f32_16x16x32_bf16 v[100:103], v[160:163], v[176:179], v[100:103]
	v_mfma_f32_16x16x32_bf16 v[88:91], v[152:155], v[184:187], v[88:91]
	v_mfma_f32_16x16x32_bf16 v[84:87], v[160:163], v[184:187], v[84:87]
	v_mfma_f32_16x16x32_bf16 v[72:75], v[152:155], v[192:195], v[72:75]
	v_mfma_f32_16x16x32_bf16 v[68:71], v[160:163], v[192:195], v[68:71]
	s_setprio 0
	s_barrier
	s_add_i32 s12, s14, s82
	v_lshl_add_u64 v[196:197], v[196:197], 0, s[68:69]
	s_mov_b32 m0, s12
	ds_read_b128 v[164:167], v243 offset:49152
	ds_read_b128 v[168:171], v243 offset:50176
	ds_read_b128 v[172:175], v243 offset:51200
	ds_read_b128 v[176:179], v243 offset:52224
	ds_read_b128 v[180:183], v243 offset:53248
	ds_read_b128 v[184:187], v243 offset:54272
	ds_read_b128 v[188:191], v243 offset:55296
	ds_read_b128 v[192:195], v243 offset:56320
	global_load_lds_dwordx4 v[196:197], off
	s_add_i32 m0, s12, 0x2000
	s_add_u32 s12, s38, 0x80080
	v_lshl_add_u64 v[196:197], v[198:199], 0, s[68:69]
	s_addc_u32 s13, s39, 0
	s_add_i32 s14, s15, s82
	global_load_lds_dwordx4 v[196:197], off
	v_lshl_add_u64 v[196:197], s[12:13], 0, v[2:3]
	s_mov_b32 m0, s14
	s_nop 0
	global_load_lds_dwordx4 v[196:197], off
	v_lshl_add_u64 v[196:197], s[12:13], 0, v[218:219]
	s_add_i32 m0, s14, 0x2000
	s_nop 0
	global_load_lds_dwordx4 v[196:197], off
	v_lshl_add_u64 v[196:197], v[200:201], 0, s[68:69]
	s_mov_b32 m0, s89
	s_nop 0
	global_load_lds_dwordx4 v[196:197], off
	v_lshl_add_u64 v[196:197], v[202:203], 0, s[68:69]
	s_mov_b32 m0, s90
	s_nop 0
	global_load_lds_dwordx4 v[196:197], off
	s_waitcnt vmcnt(8)
	s_waitcnt lgkmcnt(0)
	s_barrier
	s_setprio 1
	s_waitcnt lgkmcnt(0)
	v_mfma_f32_16x16x32_bf16 v[64:67], v[124:127], v[164:167], v[64:67]
	v_mfma_f32_16x16x32_bf16 v[60:63], v[136:139], v[164:167], v[60:63]
	v_mfma_f32_16x16x32_bf16 v[48:51], v[124:127], v[172:175], v[48:51]
	v_mfma_f32_16x16x32_bf16 v[44:47], v[136:139], v[172:175], v[44:47]
	v_mfma_f32_16x16x32_bf16 v[32:35], v[124:127], v[180:183], v[32:35]
	v_mfma_f32_16x16x32_bf16 v[28:31], v[136:139], v[180:183], v[28:31]
	v_mfma_f32_16x16x32_bf16 v[16:19], v[124:127], v[188:191], v[16:19]
	v_mfma_f32_16x16x32_bf16 v[12:15], v[136:139], v[188:191], v[12:15]
	v_mfma_f32_16x16x32_bf16 v[64:67], v[128:131], v[168:171], v[64:67]
	v_mfma_f32_16x16x32_bf16 v[60:63], v[144:147], v[168:171], v[60:63]
	v_mfma_f32_16x16x32_bf16 v[48:51], v[128:131], v[176:179], v[48:51]
	v_mfma_f32_16x16x32_bf16 v[44:47], v[144:147], v[176:179], v[44:47]
	v_mfma_f32_16x16x32_bf16 v[32:35], v[128:131], v[184:187], v[32:35]
	v_mfma_f32_16x16x32_bf16 v[28:31], v[144:147], v[184:187], v[28:31]
	v_mfma_f32_16x16x32_bf16 v[16:19], v[128:131], v[192:195], v[16:19]
	v_mfma_f32_16x16x32_bf16 v[12:15], v[144:147], v[192:195], v[12:15]
	s_setprio 0
	s_setprio 1
	v_mfma_f32_16x16x32_bf16 v[56:59], v[148:151], v[164:167], v[56:59]
	v_mfma_f32_16x16x32_bf16 v[52:55], v[156:159], v[164:167], v[52:55]
	v_mfma_f32_16x16x32_bf16 v[40:43], v[148:151], v[172:175], v[40:43]
	v_mfma_f32_16x16x32_bf16 v[36:39], v[156:159], v[172:175], v[36:39]
	v_mfma_f32_16x16x32_bf16 v[24:27], v[148:151], v[180:183], v[24:27]
	v_mfma_f32_16x16x32_bf16 v[20:23], v[156:159], v[180:183], v[20:23]
	v_mfma_f32_16x16x32_bf16 v[8:11], v[148:151], v[188:191], v[8:11]
	v_mfma_f32_16x16x32_bf16 v[4:7], v[156:159], v[188:191], v[4:7]
	v_mfma_f32_16x16x32_bf16 v[56:59], v[152:155], v[168:171], v[56:59]
	v_mfma_f32_16x16x32_bf16 v[52:55], v[160:163], v[168:171], v[52:55]
	v_mfma_f32_16x16x32_bf16 v[40:43], v[152:155], v[176:179], v[40:43]
	v_mfma_f32_16x16x32_bf16 v[36:39], v[160:163], v[176:179], v[36:39]
	v_mfma_f32_16x16x32_bf16 v[24:27], v[152:155], v[184:187], v[24:27]
	v_mfma_f32_16x16x32_bf16 v[20:23], v[160:163], v[184:187], v[20:23]
	v_mfma_f32_16x16x32_bf16 v[8:11], v[152:155], v[192:195], v[8:11]
	v_mfma_f32_16x16x32_bf16 v[4:7], v[160:163], v[192:195], v[4:7]
	s_setprio 0
	s_barrier
	s_add_i32 s11, s11, 2
	s_add_u32 s9, s9, 0x100
	s_addc_u32 s10, s10, 0
	s_add_u32 s36, s36, 0x100
	s_addc_u32 s37, s37, 0
	s_cmp_gt_u32 s11, 29
	s_cbranch_scc0 .LBB0_741
	s_nop 0
	s_nop 0
	s_nop 0

.LBB0_760:
	s_or_b64 exec, exec, s[38:39]
	s_and_b64 vcc, exec, s[46:47]
	s_cbranch_vccz .Lro_s1done
	s_barrier
.Lro_s1done:
	s_waitcnt lgkmcnt(0)
	s_barrier
	v_and_or_b32 v247, v246, 31, s93
	v_cmp_gt_i32_e64 s[38:39], 32, v246
	v_cmp_lt_i32_e32 vcc, 31, v246
	s_and_saveexec_b64 s[6:7], vcc
	s_xor_b64 s[62:63], exec, s[6:7]
	s_lshl_b32 s5, s4, 8
	v_add_u32_e32 v124, s5, v247
	v_ashrrev_i32_e32 v125, 31, v124
	v_lshlrev_b64 v[224:225], 5, v[124:125]
	s_or_saveexec_b64 s[62:63], s[62:63]
	v_mov_b32_e32 v245, s5
	v_lshl_add_u32 v244, v247, 4, 0
	s_xor_b64 exec, exec, s[62:63]
	s_cbranch_execz .LBB0_764
	v_add_u32_e32 v124, 0x20400, v244
	s_waitcnt lgkmcnt(0)
	ds_read_b128 v[124:127], v124
	s_lshl_b32 s4, s4, 8
	v_add_u32_e32 v128, s4, v247
	v_ashrrev_i32_e32 v129, 31, v128
	v_lshlrev_b64 v[224:225], 5, v[128:129]
	s_waitcnt lgkmcnt(0)
	v_mov_b32_e32 v130, v125
	v_mov_b32_e32 v131, v126
	v_mov_b32_e32 v125, v127
	v_pk_add_f32 v[124:125], v[130:131], v[124:125]
	s_ashr_i32 s55, s54, 31
	v_lshl_add_u64 v[128:129], s[42:43], 0, v[224:225]
	v_add_f32_e32 v124, v124, v125
	v_lshl_add_u64 v[128:129], s[54:55], 2, v[128:129]
	v_add_f32_e32 v124, 0xda24260, v124
	v_mov_b32_e32 v245, s4
	global_store_dword v[128:129], v124, off sc1

.LBB0_947:
	s_add_u32 s12, s38, 0xfffc0080
	s_addc_u32 s13, s39, -1
	s_add_i32 s14, 0, 0x10000
	s_cmp_eq_u32 s11, 12
	s_cselect_b32 s57, s5, s13
	s_cselect_b32 s56, s6, s12
	s_cselect_b32 s41, s7, s10
	s_cselect_b32 s40, s8, s9
	s_add_i32 s15, 0, 0x14000
	v_add_u32_e32 v144, s14, v230
	v_add_u32_e32 v160, s15, v230
	ds_read_b128 v[124:127], v144
	ds_read_b128 v[128:131], v144 offset:1024
	ds_read_b128 v[136:139], v144 offset:2048
	ds_read_b128 v[144:147], v144 offset:3072
	ds_read_b128 v[148:151], v160
	ds_read_b128 v[152:155], v160 offset:1024
	ds_read_b128 v[156:159], v160 offset:2048
	ds_read_b128 v[160:163], v160 offset:3072
	v_lshl_add_u64 v[196:197], s[38:39], 0, v[222:223]
	s_add_i32 m0, s71, 0xc000
	ds_read_b128 v[164:167], v243
	ds_read_b128 v[168:171], v243 offset:1024
	ds_read_b128 v[172:175], v243 offset:2048
	ds_read_b128 v[176:179], v243 offset:3072
	ds_read_b128 v[180:183], v243 offset:4096
	ds_read_b128 v[184:187], v243 offset:5120
	ds_read_b128 v[188:191], v243 offset:6144
	ds_read_b128 v[192:195], v243 offset:7168
	global_load_lds_dwordx4 v[196:197], off
	v_lshl_add_u64 v[196:197], s[38:39], 0, v[220:221]
	s_add_i32 m0, s71, 0xe000
	s_nop 0
	global_load_lds_dwordx4 v[196:197], off
	s_waitcnt vmcnt(8)
	s_waitcnt lgkmcnt(0)
	s_barrier
	s_setprio 1
	s_waitcnt lgkmcnt(0)
	v_mfma_f32_16x16x32_bf16 v[140:143], v[124:127], v[164:167], v[140:143]
	v_mfma_f32_16x16x32_bf16 v[132:135], v[136:139], v[164:167], v[132:135]
	v_mfma_f32_16x16x32_bf16 v[112:115], v[124:127], v[172:175], v[112:115]
	v_mfma_f32_16x16x32_bf16 v[108:111], v[136:139], v[172:175], v[108:111]
	v_mfma_f32_16x16x32_bf16 v[96:99], v[124:127], v[180:183], v[96:99]
	v_mfma_f32_16x16x32_bf16 v[92:95], v[136:139], v[180:183], v[92:95]
	v_mfma_f32_16x16x32_bf16 v[80:83], v[124:127], v[188:191], v[80:83]
	v_mfma_f32_16x16x32_bf16 v[76:79], v[136:139], v[188:191], v[76:79]
	v_mfma_f32_16x16x32_bf16 v[140:143], v[128:131], v[168:171], v[140:143]
	v_mfma_f32_16x16x32_bf16 v[132:135], v[144:147], v[168:171], v[132:135]
	v_mfma_f32_16x16x32_bf16 v[112:115], v[128:131], v[176:179], v[112:115]
	v_mfma_f32_16x16x32_bf16 v[108:111], v[144:147], v[176:179], v[108:111]
	v_mfma_f32_16x16x32_bf16 v[96:99], v[128:131], v[184:187], v[96:99]
	v_mfma_f32_16x16x32_bf16 v[92:95], v[144:147], v[184:187], v[92:95]
	v_mfma_f32_16x16x32_bf16 v[80:83], v[128:131], v[192:195], v[80:83]
	v_mfma_f32_16x16x32_bf16 v[76:79], v[144:147], v[192:195], v[76:79]
	s_setprio 0
	s_setprio 1
	v_mfma_f32_16x16x32_bf16 v[120:123], v[148:151], v[164:167], v[120:123]
	v_mfma_f32_16x16x32_bf16 v[116:119], v[156:159], v[164:167], v[116:119]
	v_mfma_f32_16x16x32_bf16 v[104:107], v[148:151], v[172:175], v[104:107]
	v_mfma_f32_16x16x32_bf16 v[100:103], v[156:159], v[172:175], v[100:103]
	v_mfma_f32_16x16x32_bf16 v[88:91], v[148:151], v[180:183], v[88:91]
	v_mfma_f32_16x16x32_bf16 v[84:87], v[156:159], v[180:183], v[84:87]
	v_mfma_f32_16x16x32_bf16 v[72:75], v[148:151], v[188:191], v[72:75]
	v_mfma_f32_16x16x32_bf16 v[68:71], v[156:159], v[188:191], v[68:71]
	v_mfma_f32_16x16x32_bf16 v[120:123], v[152:155], v[168:171], v[120:123]
	v_mfma_f32_16x16x32_bf16 v[116:119], v[160:163], v[168:171], v[116:119]
	v_mfma_f32_16x16x32_bf16 v[104:107], v[152:155], v[176:179], v[104:107]
	v_mfma_f32_16x16x32_bf16 v[100:103], v[160:163], v[176:179], v[100:103]
	v_mfma_f32_16x16x32_bf16 v[88:91], v[152:155], v[184:187], v[88:91]
	v_mfma_f32_16x16x32_bf16 v[84:87], v[160:163], v[184:187], v[84:87]
	v_mfma_f32_16x16x32_bf16 v[72:75], v[152:155], v[192:195], v[72:75]
	v_mfma_f32_16x16x32_bf16 v[68:71], v[160:163], v[192:195], v[68:71]
	s_setprio 0
	s_barrier
	s_add_i32 s12, s14, s70
	v_lshl_add_u64 v[196:197], s[40:41], 0, v[2:3]
	s_mov_b32 m0, s12
	ds_read_b128 v[164:167], v243 offset:16384
	ds_read_b128 v[168:171], v243 offset:17408
	ds_read_b128 v[172:175], v243 offset:18432
	ds_read_b128 v[176:179], v243 offset:19456
	ds_read_b128 v[180:183], v243 offset:20480
	ds_read_b128 v[184:187], v243 offset:21504
	ds_read_b128 v[188:191], v243 offset:22528
	ds_read_b128 v[192:195], v243 offset:23552
	global_load_lds_dwordx4 v[196:197], off
	s_add_i32 m0, s12, 0x2000
	s_add_u32 s12, s40, 0x40000
	v_lshl_add_u64 v[198:199], s[40:41], 0, v[218:219]
	s_addc_u32 s13, s41, 0
	s_add_i32 s14, s15, s70
	global_load_lds_dwordx4 v[198:199], off
	v_lshl_add_u64 v[200:201], s[12:13], 0, v[2:3]
	s_mov_b32 m0, s14
	v_lshl_add_u64 v[202:203], s[56:57], 0, v[216:217]
	global_load_lds_dwordx4 v[200:201], off
	v_lshl_add_u64 v[200:201], s[12:13], 0, v[218:219]
	s_add_i32 m0, s14, 0x2000
	s_nop 0
	global_load_lds_dwordx4 v[200:201], off
	v_lshl_add_u64 v[200:201], s[56:57], 0, v[0:1]
	s_mov_b32 m0, s71
	s_nop 0
	global_load_lds_dwordx4 v[200:201], off
	s_mov_b32 m0, s80
	s_nop 0
	global_load_lds_dwordx4 v[202:203], off
	s_waitcnt vmcnt(8)
	s_waitcnt lgkmcnt(0)
	s_barrier
	s_setprio 1
	s_waitcnt lgkmcnt(0)
	v_mfma_f32_16x16x32_bf16 v[64:67], v[124:127], v[164:167], v[64:67]
	v_mfma_f32_16x16x32_bf16 v[60:63], v[136:139], v[164:167], v[60:63]
	v_mfma_f32_16x16x32_bf16 v[48:51], v[124:127], v[172:175], v[48:51]
	v_mfma_f32_16x16x32_bf16 v[44:47], v[136:139], v[172:175], v[44:47]
	v_mfma_f32_16x16x32_bf16 v[32:35], v[124:127], v[180:183], v[32:35]
	v_mfma_f32_16x16x32_bf16 v[28:31], v[136:139], v[180:183], v[28:31]
	v_mfma_f32_16x16x32_bf16 v[16:19], v[124:127], v[188:191], v[16:19]
	v_mfma_f32_16x16x32_bf16 v[12:15], v[136:139], v[188:191], v[12:15]
	v_mfma_f32_16x16x32_bf16 v[64:67], v[128:131], v[168:171], v[64:67]
	v_mfma_f32_16x16x32_bf16 v[60:63], v[144:147], v[168:171], v[60:63]
	v_mfma_f32_16x16x32_bf16 v[48:51], v[128:131], v[176:179], v[48:51]
	v_mfma_f32_16x16x32_bf16 v[44:47], v[144:147], v[176:179], v[44:47]
	v_mfma_f32_16x16x32_bf16 v[32:35], v[128:131], v[184:187], v[32:35]
	v_mfma_f32_16x16x32_bf16 v[28:31], v[144:147], v[184:187], v[28:31]
	v_mfma_f32_16x16x32_bf16 v[16:19], v[128:131], v[192:195], v[16:19]
	v_mfma_f32_16x16x32_bf16 v[12:15], v[144:147], v[192:195], v[12:15]
	s_setprio 0
	s_setprio 1
	v_mfma_f32_16x16x32_bf16 v[56:59], v[148:151], v[164:167], v[56:59]
	v_mfma_f32_16x16x32_bf16 v[52:55], v[156:159], v[164:167], v[52:55]
	v_mfma_f32_16x16x32_bf16 v[40:43], v[148:151], v[172:175], v[40:43]
	v_mfma_f32_16x16x32_bf16 v[36:39], v[156:159], v[172:175], v[36:39]
	v_mfma_f32_16x16x32_bf16 v[24:27], v[148:151], v[180:183], v[24:27]
	v_mfma_f32_16x16x32_bf16 v[20:23], v[156:159], v[180:183], v[20:23]
	v_mfma_f32_16x16x32_bf16 v[8:11], v[148:151], v[188:191], v[8:11]
	v_mfma_f32_16x16x32_bf16 v[4:7], v[156:159], v[188:191], v[4:7]
	v_mfma_f32_16x16x32_bf16 v[56:59], v[152:155], v[168:171], v[56:59]
	v_mfma_f32_16x16x32_bf16 v[52:55], v[160:163], v[168:171], v[52:55]
	v_mfma_f32_16x16x32_bf16 v[40:43], v[152:155], v[176:179], v[40:43]
	v_mfma_f32_16x16x32_bf16 v[36:39], v[160:163], v[176:179], v[36:39]
	v_mfma_f32_16x16x32_bf16 v[24:27], v[152:155], v[184:187], v[24:27]
	v_mfma_f32_16x16x32_bf16 v[20:23], v[160:163], v[184:187], v[20:23]
	v_mfma_f32_16x16x32_bf16 v[8:11], v[152:155], v[192:195], v[8:11]
	v_mfma_f32_16x16x32_bf16 v[4:7], v[160:163], v[192:195], v[4:7]
	s_setprio 0
	s_barrier
	s_add_i32 s14, 0, 0x18000
	s_add_i32 s15, 0, 0x1c000
	v_add_u32_e32 v144, s14, v230
	v_add_u32_e32 v160, s15, v230
	ds_read_b128 v[124:127], v144
	ds_read_b128 v[128:131], v144 offset:1024
	ds_read_b128 v[136:139], v144 offset:2048
	ds_read_b128 v[144:147], v144 offset:3072
	ds_read_b128 v[148:151], v160
	ds_read_b128 v[152:155], v160 offset:1024
	ds_read_b128 v[156:159], v160 offset:2048
	ds_read_b128 v[160:163], v160 offset:3072
	s_add_u32 s12, s56, 0x40000
	s_addc_u32 s13, s57, 0
	s_mov_b32 m0, s81
	v_lshl_add_u64 v[204:205], s[12:13], 0, v[0:1]
	ds_read_b128 v[164:167], v243 offset:32768
	ds_read_b128 v[168:171], v243 offset:33792
	ds_read_b128 v[172:175], v243 offset:34816
	ds_read_b128 v[176:179], v243 offset:35840
	ds_read_b128 v[180:183], v243 offset:36864
	ds_read_b128 v[184:187], v243 offset:37888
	ds_read_b128 v[188:191], v243 offset:38912
	ds_read_b128 v[192:195], v243 offset:39936
	global_load_lds_dwordx4 v[204:205], off
	v_lshl_add_u64 v[204:205], s[12:13], 0, v[216:217]
	s_mov_b32 m0, s82
	s_nop 0
	global_load_lds_dwordx4 v[204:205], off
	s_waitcnt vmcnt(8)
	s_waitcnt lgkmcnt(0)
	s_barrier
	s_setprio 1
	s_waitcnt lgkmcnt(0)
	v_mfma_f32_16x16x32_bf16 v[140:143], v[124:127], v[164:167], v[140:143]
	v_mfma_f32_16x16x32_bf16 v[132:135], v[136:139], v[164:167], v[132:135]
	v_mfma_f32_16x16x32_bf16 v[112:115], v[124:127], v[172:175], v[112:115]
	v_mfma_f32_16x16x32_bf16 v[108:111], v[136:139], v[172:175], v[108:111]
	v_mfma_f32_16x16x32_bf16 v[96:99], v[124:127], v[180:183], v[96:99]
	v_mfma_f32_16x16x32_bf16 v[92:95], v[136:139], v[180:183], v[92:95]
	v_mfma_f32_16x16x32_bf16 v[80:83], v[124:127], v[188:191], v[80:83]
	v_mfma_f32_16x16x32_bf16 v[76:79], v[136:139], v[188:191], v[76:79]
	v_mfma_f32_16x16x32_bf16 v[140:143], v[128:131], v[168:171], v[140:143]
	v_mfma_f32_16x16x32_bf16 v[132:135], v[144:147], v[168:171], v[132:135]
	v_mfma_f32_16x16x32_bf16 v[112:115], v[128:131], v[176:179], v[112:115]
	v_mfma_f32_16x16x32_bf16 v[108:111], v[144:147], v[176:179], v[108:111]
	v_mfma_f32_16x16x32_bf16 v[96:99], v[128:131], v[184:187], v[96:99]
	v_mfma_f32_16x16x32_bf16 v[92:95], v[144:147], v[184:187], v[92:95]
	v_mfma_f32_16x16x32_bf16 v[80:83], v[128:131], v[192:195], v[80:83]
	v_mfma_f32_16x16x32_bf16 v[76:79], v[144:147], v[192:195], v[76:79]
	s_setprio 0
	s_setprio 1
	v_mfma_f32_16x16x32_bf16 v[120:123], v[148:151], v[164:167], v[120:123]
	v_mfma_f32_16x16x32_bf16 v[116:119], v[156:159], v[164:167], v[116:119]
	v_mfma_f32_16x16x32_bf16 v[104:107], v[148:151], v[172:175], v[104:107]
	v_mfma_f32_16x16x32_bf16 v[100:103], v[156:159], v[172:175], v[100:103]
	v_mfma_f32_16x16x32_bf16 v[88:91], v[148:151], v[180:183], v[88:91]
	v_mfma_f32_16x16x32_bf16 v[84:87], v[156:159], v[180:183], v[84:87]
	v_mfma_f32_16x16x32_bf16 v[72:75], v[148:151], v[188:191], v[72:75]
	v_mfma_f32_16x16x32_bf16 v[68:71], v[156:159], v[188:191], v[68:71]
	v_mfma_f32_16x16x32_bf16 v[120:123], v[152:155], v[168:171], v[120:123]
	v_mfma_f32_16x16x32_bf16 v[116:119], v[160:163], v[168:171], v[116:119]
	v_mfma_f32_16x16x32_bf16 v[104:107], v[152:155], v[176:179], v[104:107]
	v_mfma_f32_16x16x32_bf16 v[100:103], v[160:163], v[176:179], v[100:103]
	v_mfma_f32_16x16x32_bf16 v[88:91], v[152:155], v[184:187], v[88:91]
	v_mfma_f32_16x16x32_bf16 v[84:87], v[160:163], v[184:187], v[84:87]
	v_mfma_f32_16x16x32_bf16 v[72:75], v[152:155], v[192:195], v[72:75]
	v_mfma_f32_16x16x32_bf16 v[68:71], v[160:163], v[192:195], v[68:71]
	s_setprio 0
	s_barrier
	s_add_i32 s12, s14, s70
	v_lshl_add_u64 v[196:197], v[196:197], 0, s[68:69]
	s_mov_b32 m0, s12
	ds_read_b128 v[164:167], v243 offset:49152
	ds_read_b128 v[168:171], v243 offset:50176
	ds_read_b128 v[172:175], v243 offset:51200
	ds_read_b128 v[176:179], v243 offset:52224
	ds_read_b128 v[180:183], v243 offset:53248
	ds_read_b128 v[184:187], v243 offset:54272
	ds_read_b128 v[188:191], v243 offset:55296
	ds_read_b128 v[192:195], v243 offset:56320
	global_load_lds_dwordx4 v[196:197], off
	s_add_i32 m0, s12, 0x2000
	s_add_u32 s12, s40, 0x40080
	v_lshl_add_u64 v[196:197], v[198:199], 0, s[68:69]
	s_addc_u32 s13, s41, 0
	s_add_i32 s14, s15, s70
	global_load_lds_dwordx4 v[196:197], off
	v_lshl_add_u64 v[196:197], s[12:13], 0, v[2:3]
	s_mov_b32 m0, s14
	s_nop 0
	global_load_lds_dwordx4 v[196:197], off
	v_lshl_add_u64 v[196:197], s[12:13], 0, v[218:219]
	s_add_i32 m0, s14, 0x2000
	s_nop 0
	global_load_lds_dwordx4 v[196:197], off
	v_lshl_add_u64 v[196:197], v[200:201], 0, s[68:69]
	s_mov_b32 m0, s85
	s_nop 0
	global_load_lds_dwordx4 v[196:197], off
	v_lshl_add_u64 v[196:197], v[202:203], 0, s[68:69]
	s_mov_b32 m0, s87
	s_nop 0
	global_load_lds_dwordx4 v[196:197], off
	s_waitcnt vmcnt(8)
	s_waitcnt lgkmcnt(0)
	s_barrier
	s_setprio 1
	s_waitcnt lgkmcnt(0)
	v_mfma_f32_16x16x32_bf16 v[64:67], v[124:127], v[164:167], v[64:67]
	v_mfma_f32_16x16x32_bf16 v[60:63], v[136:139], v[164:167], v[60:63]
	v_mfma_f32_16x16x32_bf16 v[48:51], v[124:127], v[172:175], v[48:51]
	v_mfma_f32_16x16x32_bf16 v[44:47], v[136:139], v[172:175], v[44:47]
	v_mfma_f32_16x16x32_bf16 v[32:35], v[124:127], v[180:183], v[32:35]
	v_mfma_f32_16x16x32_bf16 v[28:31], v[136:139], v[180:183], v[28:31]
	v_mfma_f32_16x16x32_bf16 v[16:19], v[124:127], v[188:191], v[16:19]
	v_mfma_f32_16x16x32_bf16 v[12:15], v[136:139], v[188:191], v[12:15]
	v_mfma_f32_16x16x32_bf16 v[64:67], v[128:131], v[168:171], v[64:67]
	v_mfma_f32_16x16x32_bf16 v[60:63], v[144:147], v[168:171], v[60:63]
	v_mfma_f32_16x16x32_bf16 v[48:51], v[128:131], v[176:179], v[48:51]
	v_mfma_f32_16x16x32_bf16 v[44:47], v[144:147], v[176:179], v[44:47]
	v_mfma_f32_16x16x32_bf16 v[32:35], v[128:131], v[184:187], v[32:35]
	v_mfma_f32_16x16x32_bf16 v[28:31], v[144:147], v[184:187], v[28:31]
	v_mfma_f32_16x16x32_bf16 v[16:19], v[128:131], v[192:195], v[16:19]
	v_mfma_f32_16x16x32_bf16 v[12:15], v[144:147], v[192:195], v[12:15]
	s_setprio 0
	s_setprio 1
	v_mfma_f32_16x16x32_bf16 v[56:59], v[148:151], v[164:167], v[56:59]
	v_mfma_f32_16x16x32_bf16 v[52:55], v[156:159], v[164:167], v[52:55]
	v_mfma_f32_16x16x32_bf16 v[40:43], v[148:151], v[172:175], v[40:43]
	v_mfma_f32_16x16x32_bf16 v[36:39], v[156:159], v[172:175], v[36:39]
	v_mfma_f32_16x16x32_bf16 v[24:27], v[148:151], v[180:183], v[24:27]
	v_mfma_f32_16x16x32_bf16 v[20:23], v[156:159], v[180:183], v[20:23]
	v_mfma_f32_16x16x32_bf16 v[8:11], v[148:151], v[188:191], v[8:11]
	v_mfma_f32_16x16x32_bf16 v[4:7], v[156:159], v[188:191], v[4:7]
	v_mfma_f32_16x16x32_bf16 v[56:59], v[152:155], v[168:171], v[56:59]
	v_mfma_f32_16x16x32_bf16 v[52:55], v[160:163], v[168:171], v[52:55]
	v_mfma_f32_16x16x32_bf16 v[40:43], v[152:155], v[176:179], v[40:43]
	v_mfma_f32_16x16x32_bf16 v[36:39], v[160:163], v[176:179], v[36:39]
	v_mfma_f32_16x16x32_bf16 v[24:27], v[152:155], v[184:187], v[24:27]
	v_mfma_f32_16x16x32_bf16 v[20:23], v[160:163], v[184:187], v[20:23]
	v_mfma_f32_16x16x32_bf16 v[8:11], v[152:155], v[192:195], v[8:11]
	v_mfma_f32_16x16x32_bf16 v[4:7], v[160:163], v[192:195], v[4:7]
	s_setprio 0
	s_barrier
	s_add_i32 s11, s11, 2
	s_add_u32 s9, s9, 0x100
	s_addc_u32 s10, s10, 0
	s_add_u32 s38, s38, 0x100
	s_addc_u32 s39, s39, 0
	s_cmp_gt_u32 s11, 13
	s_cbranch_scc0 .LBB0_947
	s_nop 0
	s_nop 0
	s_nop 0

.LBB0_966:
	s_or_b64 exec, exec, s[40:41]
	s_and_b64 vcc, exec, s[46:47]
	s_cbranch_vccz .Lrp_s1done
	s_barrier
.Lrp_s1done:
	s_waitcnt lgkmcnt(0)
	s_barrier
	v_and_or_b32 v247, v246, 31, s89
	v_cmp_gt_i32_e64 s[40:41], 32, v246
	v_cmp_lt_i32_e32 vcc, 31, v246
	s_and_saveexec_b64 s[6:7], vcc
	s_xor_b64 s[56:57], exec, s[6:7]
	s_lshl_b32 s5, s4, 8
	v_add_u32_e32 v124, s5, v247
	v_ashrrev_i32_e32 v125, 31, v124
	v_lshlrev_b64 v[224:225], 5, v[124:125]
	s_or_saveexec_b64 s[56:57], s[56:57]
	v_mov_b32_e32 v245, s5
	v_lshl_add_u32 v244, v247, 4, 0
	s_xor_b64 exec, exec, s[56:57]
	s_cbranch_execz .LBB0_970
	v_add_u32_e32 v124, 0x20400, v244
	s_waitcnt lgkmcnt(0)
	ds_read_b128 v[124:127], v124
	s_lshl_b32 s4, s4, 8
	v_add_u32_e32 v128, s4, v247
	v_ashrrev_i32_e32 v129, 31, v128
	v_lshlrev_b64 v[224:225], 5, v[128:129]
	s_waitcnt lgkmcnt(0)
	v_mov_b32_e32 v130, v125
	v_mov_b32_e32 v131, v126
	v_mov_b32_e32 v125, v127
	v_pk_add_f32 v[124:125], v[130:131], v[124:125]
	s_ashr_i32 s21, s20, 31
	v_lshl_add_u64 v[128:129], s[42:43], 0, v[224:225]
	v_add_f32_e32 v124, v124, v125
	v_lshl_add_u64 v[128:129], s[20:21], 2, v[128:129]
	v_add_f32_e32 v124, 0xda24260, v124
	v_mov_b32_e32 v245, s4
	global_store_dword v[128:129], v124, off sc1

.LBB0_1134:
	s_add_u32 s40, s38, 0x100
	s_addc_u32 s41, s39, 0
	s_add_i32 s8, 0, 0x10000
	s_cmpk_eq_i32 s7, 0x54
	s_cselect_b32 s45, s61, s41
	s_cselect_b32 s44, s60, s40
	s_cselect_b32 s43, s63, s6
	s_cselect_b32 s42, s62, s5
	s_add_i32 s10, 0, 0x14000
	v_add_u32_e32 v112, s8, v242
	v_add_u32_e32 v148, s10, v242
	ds_read_b128 v[92:95], v112
	ds_read_b128 v[100:103], v112 offset:1024
	ds_read_b128 v[108:111], v112 offset:2048
	ds_read_b128 v[112:115], v112 offset:3072
	ds_read_b128 v[116:119], v148
	ds_read_b128 v[128:131], v148 offset:1024
	ds_read_b128 v[140:143], v148 offset:2048
	ds_read_b128 v[148:151], v148 offset:3072
	v_lshl_add_u64 v[196:197], s[38:39], 0, v[222:223]
	s_add_i32 m0, s83, 0xc000
	ds_read_b128 v[160:163], v245
	ds_read_b128 v[168:171], v245 offset:1024
	ds_read_b128 v[172:175], v245 offset:2048
	ds_read_b128 v[176:179], v245 offset:3072
	ds_read_b128 v[180:183], v245 offset:4096
	ds_read_b128 v[184:187], v245 offset:5120
	ds_read_b128 v[188:191], v245 offset:6144
	ds_read_b128 v[192:195], v245 offset:7168
	global_load_lds_dwordx4 v[196:197], off
	v_lshl_add_u64 v[196:197], s[38:39], 0, v[220:221]
	s_add_i32 m0, s83, 0xe000
	s_nop 0
	global_load_lds_dwordx4 v[196:197], off
	s_waitcnt vmcnt(8)
	s_waitcnt lgkmcnt(0)
	s_barrier
	s_setprio 1
	s_waitcnt lgkmcnt(0)
	v_mfma_f32_16x16x32_bf16 v[164:167], v[92:95], v[160:163], v[164:167]
	v_mfma_f32_16x16x32_bf16 v[156:159], v[108:111], v[160:163], v[156:159]
	v_mfma_f32_16x16x32_bf16 v[136:139], v[92:95], v[172:175], v[136:139]
	v_mfma_f32_16x16x32_bf16 v[132:135], v[108:111], v[172:175], v[132:135]
	v_mfma_f32_16x16x32_bf16 v[104:107], v[92:95], v[180:183], v[104:107]
	v_mfma_f32_16x16x32_bf16 v[96:99], v[108:111], v[180:183], v[96:99]
	v_mfma_f32_16x16x32_bf16 v[80:83], v[92:95], v[188:191], v[80:83]
	v_mfma_f32_16x16x32_bf16 v[76:79], v[108:111], v[188:191], v[76:79]
	v_mfma_f32_16x16x32_bf16 v[164:167], v[100:103], v[168:171], v[164:167]
	v_mfma_f32_16x16x32_bf16 v[156:159], v[112:115], v[168:171], v[156:159]
	v_mfma_f32_16x16x32_bf16 v[136:139], v[100:103], v[176:179], v[136:139]
	v_mfma_f32_16x16x32_bf16 v[132:135], v[112:115], v[176:179], v[132:135]
	v_mfma_f32_16x16x32_bf16 v[104:107], v[100:103], v[184:187], v[104:107]
	v_mfma_f32_16x16x32_bf16 v[96:99], v[112:115], v[184:187], v[96:99]
	v_mfma_f32_16x16x32_bf16 v[80:83], v[100:103], v[192:195], v[80:83]
	v_mfma_f32_16x16x32_bf16 v[76:79], v[112:115], v[192:195], v[76:79]
	s_setprio 0
	s_setprio 1
	v_mfma_f32_16x16x32_bf16 v[152:155], v[116:119], v[160:163], v[152:155]
	v_mfma_f32_16x16x32_bf16 v[144:147], v[140:143], v[160:163], v[144:147]
	v_mfma_f32_16x16x32_bf16 v[124:127], v[116:119], v[172:175], v[124:127]
	v_mfma_f32_16x16x32_bf16 v[120:123], v[140:143], v[172:175], v[120:123]
	v_mfma_f32_16x16x32_bf16 v[88:91], v[116:119], v[180:183], v[88:91]
	v_mfma_f32_16x16x32_bf16 v[84:87], v[140:143], v[180:183], v[84:87]
	v_mfma_f32_16x16x32_bf16 v[72:75], v[116:119], v[188:191], v[72:75]
	v_mfma_f32_16x16x32_bf16 v[68:71], v[140:143], v[188:191], v[68:71]
	v_mfma_f32_16x16x32_bf16 v[152:155], v[128:131], v[168:171], v[152:155]
	v_mfma_f32_16x16x32_bf16 v[144:147], v[148:151], v[168:171], v[144:147]
	v_mfma_f32_16x16x32_bf16 v[124:127], v[128:131], v[176:179], v[124:127]
	v_mfma_f32_16x16x32_bf16 v[120:123], v[148:151], v[176:179], v[120:123]
	v_mfma_f32_16x16x32_bf16 v[88:91], v[128:131], v[184:187], v[88:91]
	v_mfma_f32_16x16x32_bf16 v[84:87], v[148:151], v[184:187], v[84:87]
	v_mfma_f32_16x16x32_bf16 v[72:75], v[128:131], v[192:195], v[72:75]
	v_mfma_f32_16x16x32_bf16 v[68:71], v[148:151], v[192:195], v[68:71]
	s_setprio 0
	s_barrier
	s_add_i32 s8, s8, s82
	v_lshl_add_u64 v[196:197], s[42:43], 0, v[2:3]
	s_mov_b32 m0, s8
	ds_read_b128 v[160:163], v245 offset:16384
	ds_read_b128 v[168:171], v245 offset:17408
	ds_read_b128 v[172:175], v245 offset:18432
	ds_read_b128 v[176:179], v245 offset:19456
	ds_read_b128 v[180:183], v245 offset:20480
	ds_read_b128 v[184:187], v245 offset:21504
	ds_read_b128 v[188:191], v245 offset:22528
	ds_read_b128 v[192:195], v245 offset:23552
	global_load_lds_dwordx4 v[196:197], off
	s_add_i32 m0, s8, 0x2000
	s_add_u32 s8, s42, 0x160000
	v_lshl_add_u64 v[198:199], s[42:43], 0, v[218:219]
	s_addc_u32 s9, s43, 0
	s_add_i32 s10, s10, s82
	global_load_lds_dwordx4 v[198:199], off
	v_lshl_add_u64 v[200:201], s[8:9], 0, v[2:3]
	s_mov_b32 m0, s10
	v_lshl_add_u64 v[202:203], s[44:45], 0, v[216:217]
	global_load_lds_dwordx4 v[200:201], off
	v_lshl_add_u64 v[200:201], s[8:9], 0, v[218:219]
	s_add_i32 m0, s10, 0x2000
	s_nop 0
	global_load_lds_dwordx4 v[200:201], off
	v_lshl_add_u64 v[200:201], s[44:45], 0, v[0:1]
	s_mov_b32 m0, s83
	s_nop 0
	global_load_lds_dwordx4 v[200:201], off
	s_mov_b32 m0, s84
	s_nop 0
	global_load_lds_dwordx4 v[202:203], off
	s_waitcnt vmcnt(8)
	s_waitcnt lgkmcnt(0)
	s_barrier
	s_setprio 1
	s_waitcnt lgkmcnt(0)
	v_mfma_f32_16x16x32_bf16 v[64:67], v[92:95], v[160:163], v[64:67]
	v_mfma_f32_16x16x32_bf16 v[60:63], v[108:111], v[160:163], v[60:63]
	v_mfma_f32_16x16x32_bf16 v[48:51], v[92:95], v[172:175], v[48:51]
	v_mfma_f32_16x16x32_bf16 v[44:47], v[108:111], v[172:175], v[44:47]
	v_mfma_f32_16x16x32_bf16 v[32:35], v[92:95], v[180:183], v[32:35]
	v_mfma_f32_16x16x32_bf16 v[28:31], v[108:111], v[180:183], v[28:31]
	v_mfma_f32_16x16x32_bf16 v[16:19], v[92:95], v[188:191], v[16:19]
	v_mfma_f32_16x16x32_bf16 v[12:15], v[108:111], v[188:191], v[12:15]
	v_mfma_f32_16x16x32_bf16 v[64:67], v[100:103], v[168:171], v[64:67]
	v_mfma_f32_16x16x32_bf16 v[60:63], v[112:115], v[168:171], v[60:63]
	v_mfma_f32_16x16x32_bf16 v[48:51], v[100:103], v[176:179], v[48:51]
	v_mfma_f32_16x16x32_bf16 v[44:47], v[112:115], v[176:179], v[44:47]
	v_mfma_f32_16x16x32_bf16 v[32:35], v[100:103], v[184:187], v[32:35]
	v_mfma_f32_16x16x32_bf16 v[28:31], v[112:115], v[184:187], v[28:31]
	v_mfma_f32_16x16x32_bf16 v[16:19], v[100:103], v[192:195], v[16:19]
	v_mfma_f32_16x16x32_bf16 v[12:15], v[112:115], v[192:195], v[12:15]
	s_setprio 0
	s_setprio 1
	v_mfma_f32_16x16x32_bf16 v[56:59], v[116:119], v[160:163], v[56:59]
	v_mfma_f32_16x16x32_bf16 v[52:55], v[140:143], v[160:163], v[52:55]
	v_mfma_f32_16x16x32_bf16 v[40:43], v[116:119], v[172:175], v[40:43]
	v_mfma_f32_16x16x32_bf16 v[36:39], v[140:143], v[172:175], v[36:39]
	v_mfma_f32_16x16x32_bf16 v[24:27], v[116:119], v[180:183], v[24:27]
	v_mfma_f32_16x16x32_bf16 v[20:23], v[140:143], v[180:183], v[20:23]
	v_mfma_f32_16x16x32_bf16 v[8:11], v[116:119], v[188:191], v[8:11]
	v_mfma_f32_16x16x32_bf16 v[4:7], v[140:143], v[188:191], v[4:7]
	v_mfma_f32_16x16x32_bf16 v[56:59], v[128:131], v[168:171], v[56:59]
	v_mfma_f32_16x16x32_bf16 v[52:55], v[148:151], v[168:171], v[52:55]
	v_mfma_f32_16x16x32_bf16 v[40:43], v[128:131], v[176:179], v[40:43]
	v_mfma_f32_16x16x32_bf16 v[36:39], v[148:151], v[176:179], v[36:39]
	v_mfma_f32_16x16x32_bf16 v[24:27], v[128:131], v[184:187], v[24:27]
	v_mfma_f32_16x16x32_bf16 v[20:23], v[148:151], v[184:187], v[20:23]
	v_mfma_f32_16x16x32_bf16 v[8:11], v[128:131], v[192:195], v[8:11]
	v_mfma_f32_16x16x32_bf16 v[4:7], v[148:151], v[192:195], v[4:7]
	s_setprio 0
	s_barrier
	s_add_i32 s10, 0, 0x18000
	s_add_i32 s11, 0, 0x1c000
	v_add_u32_e32 v112, s10, v242
	v_add_u32_e32 v148, s11, v242
	ds_read_b128 v[92:95], v112
	ds_read_b128 v[100:103], v112 offset:1024
	ds_read_b128 v[108:111], v112 offset:2048
	ds_read_b128 v[112:115], v112 offset:3072
	ds_read_b128 v[116:119], v148
	ds_read_b128 v[128:131], v148 offset:1024
	ds_read_b128 v[140:143], v148 offset:2048
	ds_read_b128 v[148:151], v148 offset:3072
	s_add_u32 s8, s44, 0x160000
	s_addc_u32 s9, s45, 0
	s_mov_b32 m0, s85
	v_lshl_add_u64 v[204:205], s[8:9], 0, v[0:1]
	ds_read_b128 v[160:163], v245 offset:32768
	ds_read_b128 v[168:171], v245 offset:33792
	ds_read_b128 v[172:175], v245 offset:34816
	ds_read_b128 v[176:179], v245 offset:35840
	ds_read_b128 v[180:183], v245 offset:36864
	ds_read_b128 v[184:187], v245 offset:37888
	ds_read_b128 v[188:191], v245 offset:38912
	ds_read_b128 v[192:195], v245 offset:39936
	global_load_lds_dwordx4 v[204:205], off
	v_lshl_add_u64 v[204:205], s[8:9], 0, v[216:217]
	s_mov_b32 m0, s87
	s_nop 0
	global_load_lds_dwordx4 v[204:205], off
	s_waitcnt vmcnt(8)
	s_waitcnt lgkmcnt(0)
	s_barrier
	s_setprio 1
	s_waitcnt lgkmcnt(0)
	v_mfma_f32_16x16x32_bf16 v[164:167], v[92:95], v[160:163], v[164:167]
	v_mfma_f32_16x16x32_bf16 v[156:159], v[108:111], v[160:163], v[156:159]
	v_mfma_f32_16x16x32_bf16 v[136:139], v[92:95], v[172:175], v[136:139]
	v_mfma_f32_16x16x32_bf16 v[132:135], v[108:111], v[172:175], v[132:135]
	v_mfma_f32_16x16x32_bf16 v[104:107], v[92:95], v[180:183], v[104:107]
	v_mfma_f32_16x16x32_bf16 v[96:99], v[108:111], v[180:183], v[96:99]
	v_mfma_f32_16x16x32_bf16 v[80:83], v[92:95], v[188:191], v[80:83]
	v_mfma_f32_16x16x32_bf16 v[76:79], v[108:111], v[188:191], v[76:79]
	v_mfma_f32_16x16x32_bf16 v[164:167], v[100:103], v[168:171], v[164:167]
	v_mfma_f32_16x16x32_bf16 v[156:159], v[112:115], v[168:171], v[156:159]
	v_mfma_f32_16x16x32_bf16 v[136:139], v[100:103], v[176:179], v[136:139]
	v_mfma_f32_16x16x32_bf16 v[132:135], v[112:115], v[176:179], v[132:135]
	v_mfma_f32_16x16x32_bf16 v[104:107], v[100:103], v[184:187], v[104:107]
	v_mfma_f32_16x16x32_bf16 v[96:99], v[112:115], v[184:187], v[96:99]
	v_mfma_f32_16x16x32_bf16 v[80:83], v[100:103], v[192:195], v[80:83]
	v_mfma_f32_16x16x32_bf16 v[76:79], v[112:115], v[192:195], v[76:79]
	s_setprio 0
	s_setprio 1
	v_mfma_f32_16x16x32_bf16 v[152:155], v[116:119], v[160:163], v[152:155]
	v_mfma_f32_16x16x32_bf16 v[144:147], v[140:143], v[160:163], v[144:147]
	v_mfma_f32_16x16x32_bf16 v[124:127], v[116:119], v[172:175], v[124:127]
	v_mfma_f32_16x16x32_bf16 v[120:123], v[140:143], v[172:175], v[120:123]
	v_mfma_f32_16x16x32_bf16 v[88:91], v[116:119], v[180:183], v[88:91]
	v_mfma_f32_16x16x32_bf16 v[84:87], v[140:143], v[180:183], v[84:87]
	v_mfma_f32_16x16x32_bf16 v[72:75], v[116:119], v[188:191], v[72:75]
	v_mfma_f32_16x16x32_bf16 v[68:71], v[140:143], v[188:191], v[68:71]
	v_mfma_f32_16x16x32_bf16 v[152:155], v[128:131], v[168:171], v[152:155]
	v_mfma_f32_16x16x32_bf16 v[144:147], v[148:151], v[168:171], v[144:147]
	v_mfma_f32_16x16x32_bf16 v[124:127], v[128:131], v[176:179], v[124:127]
	v_mfma_f32_16x16x32_bf16 v[120:123], v[148:151], v[176:179], v[120:123]
	v_mfma_f32_16x16x32_bf16 v[88:91], v[128:131], v[184:187], v[88:91]
	v_mfma_f32_16x16x32_bf16 v[84:87], v[148:151], v[184:187], v[84:87]
	v_mfma_f32_16x16x32_bf16 v[72:75], v[128:131], v[192:195], v[72:75]
	v_mfma_f32_16x16x32_bf16 v[68:71], v[148:151], v[192:195], v[68:71]
	s_setprio 0
	s_barrier
	s_add_i32 s8, s10, s82
	v_lshl_add_u64 v[196:197], v[196:197], 0, s[68:69]
	s_mov_b32 m0, s8
	ds_read_b128 v[160:163], v245 offset:49152
	ds_read_b128 v[168:171], v245 offset:50176
	ds_read_b128 v[172:175], v245 offset:51200
	ds_read_b128 v[176:179], v245 offset:52224
	ds_read_b128 v[180:183], v245 offset:53248
	ds_read_b128 v[184:187], v245 offset:54272
	ds_read_b128 v[188:191], v245 offset:55296
	ds_read_b128 v[192:195], v245 offset:56320
	global_load_lds_dwordx4 v[196:197], off
	s_add_i32 m0, s8, 0x2000
	s_add_u32 s8, s42, 0x160080
	v_lshl_add_u64 v[196:197], v[198:199], 0, s[68:69]
	s_addc_u32 s9, s43, 0
	s_add_i32 s10, s11, s82
	global_load_lds_dwordx4 v[196:197], off
	v_lshl_add_u64 v[196:197], s[8:9], 0, v[2:3]
	s_mov_b32 m0, s10
	s_nop 0
	global_load_lds_dwordx4 v[196:197], off
	v_lshl_add_u64 v[196:197], s[8:9], 0, v[218:219]
	s_add_i32 m0, s10, 0x2000
	s_nop 0
	global_load_lds_dwordx4 v[196:197], off
	v_lshl_add_u64 v[196:197], v[200:201], 0, s[68:69]
	s_mov_b32 m0, s72
	s_nop 0
	global_load_lds_dwordx4 v[196:197], off
	v_lshl_add_u64 v[196:197], v[202:203], 0, s[68:69]
	s_mov_b32 m0, s88
	s_nop 0
	global_load_lds_dwordx4 v[196:197], off
	s_waitcnt vmcnt(8)
	s_waitcnt lgkmcnt(0)
	s_barrier
	s_setprio 1
	s_waitcnt lgkmcnt(0)
	v_mfma_f32_16x16x32_bf16 v[64:67], v[92:95], v[160:163], v[64:67]
	v_mfma_f32_16x16x32_bf16 v[60:63], v[108:111], v[160:163], v[60:63]
	v_mfma_f32_16x16x32_bf16 v[48:51], v[92:95], v[172:175], v[48:51]
	v_mfma_f32_16x16x32_bf16 v[44:47], v[108:111], v[172:175], v[44:47]
	v_mfma_f32_16x16x32_bf16 v[32:35], v[92:95], v[180:183], v[32:35]
	v_mfma_f32_16x16x32_bf16 v[28:31], v[108:111], v[180:183], v[28:31]
	v_mfma_f32_16x16x32_bf16 v[16:19], v[92:95], v[188:191], v[16:19]
	v_mfma_f32_16x16x32_bf16 v[12:15], v[108:111], v[188:191], v[12:15]
	v_mfma_f32_16x16x32_bf16 v[64:67], v[100:103], v[168:171], v[64:67]
	v_mfma_f32_16x16x32_bf16 v[60:63], v[112:115], v[168:171], v[60:63]
	v_mfma_f32_16x16x32_bf16 v[48:51], v[100:103], v[176:179], v[48:51]
	v_mfma_f32_16x16x32_bf16 v[44:47], v[112:115], v[176:179], v[44:47]
	v_mfma_f32_16x16x32_bf16 v[32:35], v[100:103], v[184:187], v[32:35]
	v_mfma_f32_16x16x32_bf16 v[28:31], v[112:115], v[184:187], v[28:31]
	v_mfma_f32_16x16x32_bf16 v[16:19], v[100:103], v[192:195], v[16:19]
	v_mfma_f32_16x16x32_bf16 v[12:15], v[112:115], v[192:195], v[12:15]
	s_setprio 0
	s_setprio 1
	v_mfma_f32_16x16x32_bf16 v[56:59], v[116:119], v[160:163], v[56:59]
	v_mfma_f32_16x16x32_bf16 v[52:55], v[140:143], v[160:163], v[52:55]
	v_mfma_f32_16x16x32_bf16 v[40:43], v[116:119], v[172:175], v[40:43]
	v_mfma_f32_16x16x32_bf16 v[36:39], v[140:143], v[172:175], v[36:39]
	v_mfma_f32_16x16x32_bf16 v[24:27], v[116:119], v[180:183], v[24:27]
	v_mfma_f32_16x16x32_bf16 v[20:23], v[140:143], v[180:183], v[20:23]
	v_mfma_f32_16x16x32_bf16 v[8:11], v[116:119], v[188:191], v[8:11]
	v_mfma_f32_16x16x32_bf16 v[4:7], v[140:143], v[188:191], v[4:7]
	v_mfma_f32_16x16x32_bf16 v[56:59], v[128:131], v[168:171], v[56:59]
	v_mfma_f32_16x16x32_bf16 v[52:55], v[148:151], v[168:171], v[52:55]
	v_mfma_f32_16x16x32_bf16 v[40:43], v[128:131], v[176:179], v[40:43]
	v_mfma_f32_16x16x32_bf16 v[36:39], v[148:151], v[176:179], v[36:39]
	v_mfma_f32_16x16x32_bf16 v[24:27], v[128:131], v[184:187], v[24:27]
	v_mfma_f32_16x16x32_bf16 v[20:23], v[148:151], v[184:187], v[20:23]
	v_mfma_f32_16x16x32_bf16 v[8:11], v[128:131], v[192:195], v[8:11]
	v_mfma_f32_16x16x32_bf16 v[4:7], v[148:151], v[192:195], v[4:7]
	s_setprio 0
	s_barrier
	s_add_i32 s7, s7, 2
	s_add_u32 s5, s5, 0x100
	s_addc_u32 s6, s6, 0
	s_cmpk_gt_u32 s7, 0x55
	s_mov_b64 s[38:39], s[40:41]
	s_cbranch_scc0 .LBB0_1134
	s_nop 0
	s_nop 0
	s_nop 0

.LBB0_1153:
	s_or_b64 exec, exec, s[40:41]
	s_and_b64 vcc, exec, s[52:53]
	s_cbranch_vccz .Lrd_s1done
	s_barrier
.Lrd_s1done:
	s_waitcnt lgkmcnt(0)
	s_barrier
	v_and_or_b32 v249, v248, 31, s91
	v_cmp_gt_i32_e64 s[40:41], 32, v248
	v_cmp_lt_i32_e32 vcc, 31, v248
	s_and_saveexec_b64 s[6:7], vcc
	s_xor_b64 s[42:43], exec, s[6:7]
	s_lshl_b32 s5, s4, 8
	v_add_u32_e32 v92, s5, v249
	v_ashrrev_i32_e32 v93, 31, v92
	v_lshlrev_b64 v[224:225], 5, v[92:93]
	s_or_saveexec_b64 s[42:43], s[42:43]
	v_mov_b32_e32 v247, s5
	v_lshl_add_u32 v246, v249, 4, 0
	s_xor_b64 exec, exec, s[42:43]
	s_cbranch_execz .LBB0_1157
	v_add_u32_e32 v92, 0x20400, v246
	s_waitcnt lgkmcnt(0)
	ds_read_b128 v[92:95], v92
	s_lshl_b32 s4, s4, 8
	v_add_u32_e32 v100, s4, v249
	v_ashrrev_i32_e32 v101, 31, v100
	v_lshlrev_b64 v[224:225], 5, v[100:101]
	s_waitcnt lgkmcnt(0)
	v_mov_b32_e32 v102, v93
	v_mov_b32_e32 v103, v94
	v_mov_b32_e32 v93, v95
	v_pk_add_f32 v[92:93], v[102:103], v[92:93]
	s_ashr_i32 s21, s20, 31
	v_lshl_add_u64 v[100:101], s[48:49], 0, v[224:225]
	v_add_f32_e32 v92, v92, v93
	v_lshl_add_u64 v[100:101], s[20:21], 2, v[100:101]
	v_add_f32_e32 v92, 0xda24260, v92
	v_mov_b32_e32 v247, s4
	global_store_dword v[100:101], v92, off sc1
